# v109 with the now-pointless counted vmcnt waits in the norm row blocks dropped (rows no longer wait for earlier rows' store acks)
# baseline (speedup 1.0000x reference)
.LBB0_475:
	s_or_b64 exec, exec, s[36:37]
	s_waitcnt vmcnt(0)
	v_mul_f32_e32 v0, v63, v63
	v_mul_f32_e32 v67, v51, v51
	v_fmac_f32_e32 v0, v62, v62
	v_fmac_f32_e32 v67, v50, v50
	v_fmac_f32_e32 v0, v64, v64
	v_fmac_f32_e32 v67, v52, v52
	v_fmac_f32_e32 v0, v65, v65
	v_fmac_f32_e32 v67, v53, v53
	v_add_f32_e32 v0, v67, v0
	v_mul_f32_e32 v67, v47, v47
	v_fmac_f32_e32 v67, v46, v46
	v_fmac_f32_e32 v67, v48, v48
	v_fmac_f32_e32 v67, v49, v49
	v_add_f32_e32 v0, v67, v0
	v_mul_f32_e32 v67, v31, v31
	v_fmac_f32_e32 v67, v30, v30
	v_fmac_f32_e32 v67, v32, v32
	v_fmac_f32_e32 v67, v33, v33
	v_add_f32_e32 v0, v67, v0
	v_min_i32_e32 v67, 0x8000, v66
	v_ashrrev_i32_e32 v67, 12, v67
	v_lshl_add_u32 v222, v67, 13, v223
	v_mul_i32_i24_e32 v98, 0x1800, v67
	v_ashrrev_i32_e32 v99, 31, v98
	v_lshl_add_u64 v[100:101], v[98:99], 2, s[22:23]
	s_mov_b64 s[10:11], 0x1000
	v_lshl_add_u64 v[98:99], v[100:101], 0, s[10:11]
	v_mov_b32_e32 v85, v1
	v_lshl_add_u64 v[106:107], v[98:99], 0, v[84:85]
	ds_read_b128 v[102:105], v242
	ds_read_b128 v[114:117], v222 offset:4096
	v_lshl_add_u64 v[100:101], v[100:101], 0, v[84:85]
	ds_read_b128 v[118:121], v222
	v_mov_b32_e32 v87, v1
	v_mov_b32_e32 v89, v1
	v_mov_b32_e32 v91, v1
	ds_read_b128 v[168:171], v242 offset:1024
	v_lshl_add_u64 v[172:173], v[98:99], 0, v[86:87]
	ds_read_b128 v[172:175], v222 offset:5120
	ds_read_b128 v[176:179], v222 offset:1024
	ds_read_b128 v[180:183], v242 offset:2048
	v_lshl_add_u64 v[184:185], v[98:99], 0, v[88:89]
	ds_read_b128 v[184:187], v222 offset:6144
	ds_read_b128 v[188:191], v222 offset:2048
	ds_read_b128 v[192:195], v242 offset:3072
	v_lshl_add_u64 v[196:197], v[98:99], 0, v[90:91]
	ds_read_b128 v[196:199], v222 offset:7168
	ds_read_b128 v[200:203], v222 offset:3072
	ds_bpermute_b32 v67, v108, v0
	v_mov_b32_e32 v87, v1
	v_mov_b32_e32 v89, v1
	v_mov_b32_e32 v91, v1
	s_waitcnt lgkmcnt(0)
	v_add_f32_e32 v0, v0, v67
	ds_bpermute_b32 v67, v109, v0
	s_waitcnt lgkmcnt(0)
	v_add_f32_e32 v0, v0, v67
	ds_bpermute_b32 v67, v110, v0
	s_waitcnt lgkmcnt(0)
	v_add_f32_e32 v0, v0, v67
	ds_bpermute_b32 v67, v111, v0
	s_waitcnt lgkmcnt(0)
	v_add_f32_e32 v0, v0, v67
	ds_bpermute_b32 v67, v112, v0
	s_waitcnt lgkmcnt(0)
	v_add_f32_e32 v0, v0, v67
	ds_bpermute_b32 v67, v113, v0
	s_waitcnt lgkmcnt(0)
	v_add_f32_e32 v0, v0, v67
	v_fmamk_f32 v0, v0, 0x3a800000, v218
	v_cmp_gt_f32_e32 vcc, s13, v0
	v_mul_f32_e32 v67, 0x4b800000, v0
	s_nop 0
	v_cndmask_b32_e32 v0, v0, v67, vcc
	v_rsq_f32_e32 v0, v0
	s_nop 0
	v_mul_f32_e32 v67, 0x45800000, v0
	v_cndmask_b32_e32 v0, v0, v67, vcc
	v_pk_mul_f32 v[64:65], v[64:65], v[0:1] op_sel_hi:[1,0]
	v_pk_mul_f32 v[62:63], v[62:63], v[0:1] op_sel_hi:[1,0]
	v_pk_mul_f32 v[52:53], v[52:53], v[0:1] op_sel_hi:[1,0]
	v_pk_mul_f32 v[50:51], v[50:51], v[0:1] op_sel_hi:[1,0]
	v_pk_mul_f32 v[48:49], v[48:49], v[0:1] op_sel_hi:[1,0]
	v_pk_mul_f32 v[46:47], v[46:47], v[0:1] op_sel_hi:[1,0]
	v_pk_mul_f32 v[32:33], v[32:33], v[0:1] op_sel_hi:[1,0]
	v_pk_mul_f32 v[30:31], v[30:31], v[0:1] op_sel_hi:[1,0]
	v_cmp_gt_i32_e32 vcc, s4, v96
	s_waitcnt lgkmcnt(0)
	v_pk_mul_f32 v[62:63], v[102:103], v[62:63]
	v_pk_mul_f32 v[64:65], v[104:105], v[64:65]
	s_waitcnt lgkmcnt(0)
	v_pk_add_f32 v[102:103], v[116:117], 1.0 op_sel_hi:[1,0]
	v_pk_add_f32 v[104:105], v[114:115], 1.0 op_sel_hi:[1,0]
	s_waitcnt lgkmcnt(0)
	v_pk_fma_f32 v[64:65], v[102:103], v[64:65], v[120:121]
	v_pk_fma_f32 v[62:63], v[104:105], v[62:63], v[118:119]
	v_lshl_add_u64 v[102:103], v[98:99], 0, v[86:87]
	v_cvt_pk_bf16_f32 v62, v62, v63
	v_cvt_pk_bf16_f32 v63, v64, v65
	global_store_dwordx2 v[82:83], v[62:63], off
	s_waitcnt lgkmcnt(0)
	v_pk_mul_f32 v[50:51], v[168:169], v[50:51]
	v_pk_mul_f32 v[52:53], v[170:171], v[52:53]
	v_pk_add_f32 v[62:63], v[174:175], 1.0 op_sel_hi:[1, 0]
	v_pk_add_f32 v[64:65], v[172:173], 1.0 op_sel_hi:[1, 0]
	v_pk_fma_f32 v[52:53], v[62:63], v[52:53], v[178:179]
	v_pk_fma_f32 v[50:51], v[64:65], v[50:51], v[176:177]
	v_lshl_add_u64 v[62:63], v[98:99], 0, v[88:89]
	v_cvt_pk_bf16_f32 v50, v50, v51
	v_cvt_pk_bf16_f32 v51, v52, v53
	global_store_dwordx2 v[82:83], v[50:51], off offset:512
	s_waitcnt lgkmcnt(0)
	v_pk_mul_f32 v[46:47], v[180:181], v[46:47]
	v_pk_mul_f32 v[48:49], v[182:183], v[48:49]
	v_pk_add_f32 v[50:51], v[186:187], 1.0 op_sel_hi:[1, 0]
	v_pk_add_f32 v[52:53], v[184:185], 1.0 op_sel_hi:[1, 0]
	v_pk_fma_f32 v[48:49], v[50:51], v[48:49], v[190:191]
	v_pk_fma_f32 v[46:47], v[52:53], v[46:47], v[188:189]
	v_lshl_add_u64 v[50:51], v[98:99], 0, v[90:91]
	v_cvt_pk_bf16_f32 v46, v46, v47
	v_cvt_pk_bf16_f32 v47, v48, v49
	global_store_dwordx2 v[82:83], v[46:47], off offset:1024
	s_waitcnt lgkmcnt(0)
	v_pk_mul_f32 v[30:31], v[30:31], v[192:193]
	v_pk_mul_f32 v[32:33], v[32:33], v[194:195]
	v_pk_add_f32 v[46:47], v[198:199], 1.0 op_sel_hi:[1, 0]
	v_pk_add_f32 v[48:49], v[196:197], 1.0 op_sel_hi:[1, 0]
	v_pk_fma_f32 v[32:33], v[32:33], v[46:47], v[202:203]
	v_pk_fma_f32 v[30:31], v[30:31], v[48:49], v[200:201]
	s_nop 0
	v_cvt_pk_bf16_f32 v30, v30, v31
	v_cvt_pk_bf16_f32 v31, v32, v33
	global_store_dwordx2 v[82:83], v[30:31], off offset:1536
	s_and_saveexec_b64 s[36:37], vcc
	s_cbranch_execz .LBB0_478
	v_mul_f32_e32 v0, v59, v59
	v_mul_f32_e32 v30, v43, v43
	v_fmac_f32_e32 v0, v58, v58
	v_fmac_f32_e32 v30, v42, v42
	v_fmac_f32_e32 v0, v60, v60
	v_fmac_f32_e32 v30, v44, v44
	v_fmac_f32_e32 v0, v61, v61
	v_fmac_f32_e32 v30, v45, v45
	v_add_f32_e32 v0, v30, v0
	v_mul_f32_e32 v30, v39, v39
	v_fmac_f32_e32 v30, v38, v38
	v_fmac_f32_e32 v30, v40, v40
	v_fmac_f32_e32 v30, v41, v41
	v_add_f32_e32 v0, v30, v0
	v_mul_f32_e32 v30, v35, v35
	v_fmac_f32_e32 v30, v34, v34
	v_fmac_f32_e32 v30, v36, v36
	v_fmac_f32_e32 v30, v37, v37
	v_add_f32_e32 v0, v30, v0
	ds_bpermute_b32 v46, v108, v0
	v_min_i32_e32 v30, 0x8000, v96
	v_ashrrev_i32_e32 v30, 12, v30
	v_lshl_add_u32 v222, v30, 13, v223
	v_mul_i32_i24_e32 v30, 0x1800, v30
	v_ashrrev_i32_e32 v31, 31, v30
	s_waitcnt lgkmcnt(0)
	v_add_f32_e32 v0, v0, v46
	ds_bpermute_b32 v46, v109, v0
	v_lshl_add_u64 v[32:33], v[30:31], 2, s[22:23]
	v_lshl_add_u64 v[30:31], v[32:33], 0, s[10:11]
	v_lshl_add_u64 v[52:53], v[30:31], 0, v[84:85]
	v_ashrrev_i32_e32 v97, 31, v96
	s_waitcnt lgkmcnt(0)
	v_add_f32_e32 v0, v0, v46
	ds_bpermute_b32 v46, v110, v0
	ds_read_b128 v[48:51], v242
	ds_read_b128 v[62:65], v222 offset:4096
	v_lshl_add_u64 v[32:33], v[32:33], 0, v[84:85]
	s_waitcnt lgkmcnt(0)
	v_add_f32_e32 v0, v0, v46
	ds_bpermute_b32 v46, v111, v0
	s_waitcnt lgkmcnt(0)
	v_add_f32_e32 v0, v0, v46
	ds_bpermute_b32 v46, v112, v0
	s_waitcnt lgkmcnt(0)
	v_add_f32_e32 v0, v0, v46
	ds_bpermute_b32 v46, v113, v0
	s_waitcnt lgkmcnt(0)
	v_add_f32_e32 v0, v0, v46
	v_fmamk_f32 v0, v0, 0x3a800000, v218
	v_cmp_gt_f32_e32 vcc, s13, v0
	v_mul_f32_e32 v46, 0x4b800000, v0
	s_nop 0
	v_cndmask_b32_e32 v0, v0, v46, vcc
	v_rsq_f32_e32 v0, v0
	s_nop 0
	v_mul_f32_e32 v46, 0x45800000, v0
	v_cndmask_b32_e32 v0, v0, v46, vcc
	v_lshlrev_b64 v[46:47], 11, v[96:97]
	ds_read_b128 v[96:99], v222
	v_mov_b32_e32 v87, v1
	v_mov_b32_e32 v89, v1
	v_mov_b32_e32 v91, v1
	ds_read_b128 v[168:171], v242 offset:1024
	v_lshl_add_u64 v[172:173], v[30:31], 0, v[86:87]
	ds_read_b128 v[172:175], v222 offset:5120
	ds_read_b128 v[176:179], v222 offset:1024
	ds_read_b128 v[180:183], v242 offset:2048
	v_lshl_add_u64 v[184:185], v[30:31], 0, v[88:89]
	ds_read_b128 v[184:187], v222 offset:6144
	ds_read_b128 v[188:191], v222 offset:2048
	ds_read_b128 v[192:195], v242 offset:3072
	v_lshl_add_u64 v[196:197], v[30:31], 0, v[90:91]
	ds_read_b128 v[196:199], v222 offset:7168
	ds_read_b128 v[200:203], v222 offset:3072
	v_pk_mul_f32 v[52:53], v[60:61], v[0:1] op_sel_hi:[1,0]
	v_pk_mul_f32 v[58:59], v[58:59], v[0:1] op_sel_hi:[1,0]
	v_pk_mul_f32 v[44:45], v[44:45], v[0:1] op_sel_hi:[1,0]
	v_pk_mul_f32 v[42:43], v[42:43], v[0:1] op_sel_hi:[1,0]
	v_pk_mul_f32 v[40:41], v[40:41], v[0:1] op_sel_hi:[1,0]
	v_pk_mul_f32 v[38:39], v[38:39], v[0:1] op_sel_hi:[1,0]
	v_pk_mul_f32 v[36:37], v[36:37], v[0:1] op_sel_hi:[1,0]
	v_pk_mul_f32 v[34:35], v[34:35], v[0:1] op_sel_hi:[1,0]
	s_waitcnt lgkmcnt(0)
	v_pk_mul_f32 v[48:49], v[48:49], v[58:59]
	v_pk_mul_f32 v[50:51], v[50:51], v[52:53]
	s_waitcnt lgkmcnt(0)
	v_pk_add_f32 v[52:53], v[64:65], 1.0 op_sel_hi:[1,0]
	v_pk_add_f32 v[58:59], v[62:63], 1.0 op_sel_hi:[1,0]
	v_lshl_add_u64 v[62:63], v[80:81], 0, v[46:47]
	s_waitcnt lgkmcnt(0)
	v_pk_fma_f32 v[50:51], v[52:53], v[50:51], v[98:99]
	v_pk_fma_f32 v[48:49], v[58:59], v[48:49], v[96:97]
	s_nop 0
	v_cvt_pk_bf16_f32 v48, v48, v49
	v_cvt_pk_bf16_f32 v49, v50, v51
	global_store_dwordx2 v[62:63], v[48:49], off
	v_lshl_add_u64 v[50:51], v[30:31], 0, v[86:87]
	s_waitcnt lgkmcnt(0)
	v_pk_mul_f32 v[42:43], v[168:169], v[42:43]
	v_pk_mul_f32 v[44:45], v[170:171], v[44:45]
	v_pk_add_f32 v[46:47], v[174:175], 1.0 op_sel_hi:[1, 0]
	v_pk_add_f32 v[48:49], v[172:173], 1.0 op_sel_hi:[1, 0]
	v_pk_fma_f32 v[44:45], v[46:47], v[44:45], v[178:179]
	v_pk_fma_f32 v[42:43], v[48:49], v[42:43], v[176:177]
	v_lshl_add_u64 v[46:47], v[30:31], 0, v[88:89]
	v_cvt_pk_bf16_f32 v42, v42, v43
	v_cvt_pk_bf16_f32 v43, v44, v45
	global_store_dwordx2 v[62:63], v[42:43], off offset:512
	v_lshl_add_u64 v[30:31], v[30:31], 0, v[90:91]
	s_waitcnt lgkmcnt(0)
	v_pk_mul_f32 v[38:39], v[180:181], v[38:39]
	v_pk_mul_f32 v[40:41], v[182:183], v[40:41]
	v_pk_add_f32 v[42:43], v[186:187], 1.0 op_sel_hi:[1, 0]
	v_pk_add_f32 v[44:45], v[184:185], 1.0 op_sel_hi:[1, 0]
	v_pk_fma_f32 v[40:41], v[42:43], v[40:41], v[190:191]
	v_pk_fma_f32 v[38:39], v[44:45], v[38:39], v[188:189]
	s_nop 0
	v_cvt_pk_bf16_f32 v38, v38, v39
	v_cvt_pk_bf16_f32 v39, v40, v41
	global_store_dwordx2 v[62:63], v[38:39], off offset:1024
	s_waitcnt lgkmcnt(0)
	v_pk_mul_f32 v[34:35], v[34:35], v[192:193]
	v_pk_mul_f32 v[36:37], v[36:37], v[194:195]
	v_pk_add_f32 v[38:39], v[198:199], 1.0 op_sel_hi:[1, 0]
	v_pk_add_f32 v[40:41], v[196:197], 1.0 op_sel_hi:[1, 0]
	v_pk_fma_f32 v[32:33], v[36:37], v[38:39], v[202:203]
	v_pk_fma_f32 v[30:31], v[34:35], v[40:41], v[200:201]
	s_nop 0
	v_cvt_pk_bf16_f32 v30, v30, v31
	v_cvt_pk_bf16_f32 v31, v32, v33
	global_store_dwordx2 v[62:63], v[30:31], off offset:1536
	s_or_b64 exec, exec, s[36:37]
	v_cmp_gt_i32_e32 vcc, s4, v94
	s_and_saveexec_b64 s[36:37], vcc
	s_cbranch_execnz .LBB0_479

.LBB0_479:
	v_mul_f32_e32 v0, v55, v55
	v_mul_f32_e32 v30, v27, v27
	v_fmac_f32_e32 v0, v54, v54
	v_fmac_f32_e32 v30, v26, v26
	v_fmac_f32_e32 v0, v56, v56
	v_fmac_f32_e32 v30, v28, v28
	v_fmac_f32_e32 v0, v57, v57
	v_fmac_f32_e32 v30, v29, v29
	v_add_f32_e32 v0, v30, v0
	v_mul_f32_e32 v30, v19, v19
	v_fmac_f32_e32 v30, v18, v18
	v_fmac_f32_e32 v30, v20, v20
	v_fmac_f32_e32 v30, v21, v21
	v_add_f32_e32 v0, v30, v0
	v_mul_f32_e32 v30, v15, v15
	v_fmac_f32_e32 v30, v14, v14
	v_fmac_f32_e32 v30, v16, v16
	v_fmac_f32_e32 v30, v17, v17
	v_add_f32_e32 v0, v30, v0
	v_min_i32_e32 v30, 0x8000, v94
	v_ashrrev_i32_e32 v30, 12, v30
	v_lshl_add_u32 v222, v30, 13, v223
	v_mul_i32_i24_e32 v30, 0x1800, v30
	v_ashrrev_i32_e32 v31, 31, v30
	v_lshl_add_u64 v[36:37], v[30:31], 2, s[22:23]
	ds_bpermute_b32 v30, v108, v0
	v_lshl_add_u64 v[34:35], v[36:37], 0, s[10:11]
	v_mov_b32_e32 v85, v1
	v_lshl_add_u64 v[38:39], v[34:35], 0, v[84:85]
	ds_read_b128 v[40:43], v222 offset:4096
	s_waitcnt lgkmcnt(0)
	v_add_f32_e32 v0, v0, v30
	ds_bpermute_b32 v30, v109, v0
	v_lshl_add_u64 v[38:39], v[36:37], 0, v[84:85]
	ds_read_b128 v[44:47], v222
	v_ashrrev_i32_e32 v95, 31, v94
	v_lshlrev_b64 v[48:49], 11, v[94:95]
	s_waitcnt lgkmcnt(0)
	v_add_f32_e32 v0, v0, v30
	ds_bpermute_b32 v30, v110, v0
	v_mov_b32_e32 v87, v1
	v_mov_b32_e32 v89, v1
	v_mov_b32_e32 v91, v1
	s_waitcnt lgkmcnt(0)
	v_add_f32_e32 v0, v0, v30
	ds_bpermute_b32 v30, v111, v0
	s_waitcnt lgkmcnt(0)
	v_add_f32_e32 v0, v0, v30
	ds_bpermute_b32 v30, v112, v0
	s_waitcnt lgkmcnt(0)
	v_add_f32_e32 v0, v0, v30
	ds_bpermute_b32 v30, v113, v0
	s_waitcnt lgkmcnt(0)
	v_add_f32_e32 v0, v0, v30
	v_fmamk_f32 v0, v0, 0x3a800000, v218
	v_cmp_gt_f32_e32 vcc, s13, v0
	v_mul_f32_e32 v30, 0x4b800000, v0
	s_waitcnt lgkmcnt(0)
	v_pk_add_f32 v[40:41], v[40:41], 1.0 op_sel_hi:[1,0]
	v_cndmask_b32_e32 v0, v0, v30, vcc
	v_rsq_f32_e32 v0, v0
	s_nop 0
	v_mul_f32_e32 v30, 0x45800000, v0
	v_cndmask_b32_e32 v0, v0, v30, vcc
	ds_read_b128 v[30:33], v242
	v_mov_b32_e32 v87, v1
	v_mov_b32_e32 v89, v1
	v_mov_b32_e32 v91, v1
	ds_read_b128 v[168:171], v242 offset:1024
	v_lshl_add_u64 v[172:173], v[34:35], 0, v[86:87]
	ds_read_b128 v[172:175], v222 offset:5120
	ds_read_b128 v[176:179], v222 offset:1024
	ds_read_b128 v[180:183], v242 offset:2048
	v_lshl_add_u64 v[184:185], v[34:35], 0, v[88:89]
	ds_read_b128 v[184:187], v222 offset:6144
	ds_read_b128 v[188:191], v222 offset:2048
	ds_read_b128 v[192:195], v242 offset:3072
	v_lshl_add_u64 v[196:197], v[34:35], 0, v[90:91]
	ds_read_b128 v[196:199], v222 offset:7168
	ds_read_b128 v[200:203], v222 offset:3072
	v_pk_mul_f32 v[36:37], v[56:57], v[0:1] op_sel_hi:[1,0]
	v_pk_mul_f32 v[50:51], v[54:55], v[0:1] op_sel_hi:[1,0]
	v_pk_mul_f32 v[28:29], v[28:29], v[0:1] op_sel_hi:[1,0]
	v_pk_mul_f32 v[26:27], v[26:27], v[0:1] op_sel_hi:[1,0]
	v_pk_mul_f32 v[20:21], v[20:21], v[0:1] op_sel_hi:[1,0]
	v_pk_mul_f32 v[18:19], v[18:19], v[0:1] op_sel_hi:[1,0]
	v_pk_mul_f32 v[16:17], v[16:17], v[0:1] op_sel_hi:[1,0]
	v_pk_mul_f32 v[14:15], v[14:15], v[0:1] op_sel_hi:[1,0]
	s_waitcnt lgkmcnt(0)
	v_pk_mul_f32 v[30:31], v[30:31], v[50:51]
	v_pk_mul_f32 v[32:33], v[32:33], v[36:37]
	v_pk_add_f32 v[36:37], v[42:43], 1.0 op_sel_hi:[1,0]
	v_pk_fma_f32 v[30:31], v[40:41], v[30:31], v[44:45]
	v_pk_fma_f32 v[32:33], v[36:37], v[32:33], v[46:47]
	v_cvt_pk_bf16_f32 v30, v30, v31
	v_cvt_pk_bf16_f32 v31, v32, v33
	v_lshl_add_u64 v[36:37], v[80:81], 0, v[48:49]
	global_store_dwordx2 v[36:37], v[30:31], off
	v_lshl_add_u64 v[40:41], v[34:35], 0, v[86:87]
	s_waitcnt lgkmcnt(0)
	v_pk_mul_f32 v[26:27], v[168:169], v[26:27]
	v_pk_mul_f32 v[28:29], v[170:171], v[28:29]
	v_pk_add_f32 v[30:31], v[174:175], 1.0 op_sel_hi:[1, 0]
	v_pk_add_f32 v[32:33], v[172:173], 1.0 op_sel_hi:[1, 0]
	v_pk_fma_f32 v[28:29], v[30:31], v[28:29], v[178:179]
	v_pk_fma_f32 v[26:27], v[32:33], v[26:27], v[176:177]
	v_lshl_add_u64 v[30:31], v[34:35], 0, v[88:89]
	v_cvt_pk_bf16_f32 v26, v26, v27
	v_cvt_pk_bf16_f32 v27, v28, v29
	global_store_dwordx2 v[36:37], v[26:27], off offset:512
	s_waitcnt lgkmcnt(0)
	v_pk_mul_f32 v[18:19], v[180:181], v[18:19]
	v_pk_mul_f32 v[20:21], v[182:183], v[20:21]
	v_pk_add_f32 v[26:27], v[186:187], 1.0 op_sel_hi:[1, 0]
	v_pk_add_f32 v[28:29], v[184:185], 1.0 op_sel_hi:[1, 0]
	v_pk_fma_f32 v[20:21], v[26:27], v[20:21], v[190:191]
	v_pk_fma_f32 v[18:19], v[28:29], v[18:19], v[188:189]
	v_lshl_add_u64 v[26:27], v[34:35], 0, v[90:91]
	v_cvt_pk_bf16_f32 v18, v18, v19
	v_cvt_pk_bf16_f32 v19, v20, v21
	global_store_dwordx2 v[36:37], v[18:19], off offset:1024
	s_waitcnt lgkmcnt(0)
	v_pk_mul_f32 v[14:15], v[14:15], v[192:193]
	v_pk_mul_f32 v[16:17], v[16:17], v[194:195]
	v_pk_add_f32 v[18:19], v[198:199], 1.0 op_sel_hi:[1, 0]
	v_pk_add_f32 v[20:21], v[196:197], 1.0 op_sel_hi:[1, 0]
	v_pk_fma_f32 v[16:17], v[16:17], v[18:19], v[202:203]
	v_pk_fma_f32 v[14:15], v[14:15], v[20:21], v[200:201]
	s_nop 0
	v_cvt_pk_bf16_f32 v14, v14, v15
	v_cvt_pk_bf16_f32 v15, v16, v17
	global_store_dwordx2 v[36:37], v[14:15], off offset:1536
	s_or_b64 exec, exec, s[36:37]
	v_cmp_gt_i32_e32 vcc, s4, v92
	s_and_saveexec_b64 s[36:37], vcc
	s_cbranch_execz .LBB0_442
.LBB0_480:
	v_mul_f32_e32 v0, v23, v23
	v_mul_f32_e32 v14, v11, v11
	v_fmac_f32_e32 v0, v22, v22
	v_fmac_f32_e32 v14, v10, v10
	v_fmac_f32_e32 v0, v24, v24
	v_fmac_f32_e32 v14, v12, v12
	v_fmac_f32_e32 v0, v25, v25
	v_fmac_f32_e32 v14, v13, v13
	v_add_f32_e32 v0, v14, v0
	v_mul_f32_e32 v14, v7, v7
	v_fmac_f32_e32 v14, v6, v6
	v_fmac_f32_e32 v14, v8, v8
	v_fmac_f32_e32 v14, v9, v9
	v_add_f32_e32 v0, v14, v0
	v_mul_f32_e32 v14, v3, v3
	v_fmac_f32_e32 v14, v2, v2
	v_fmac_f32_e32 v14, v4, v4
	v_fmac_f32_e32 v14, v5, v5
	v_add_f32_e32 v0, v14, v0
	v_min_i32_e32 v14, 0x8000, v92
	v_ashrrev_i32_e32 v14, 12, v14
	v_lshl_add_u32 v222, v14, 13, v223
	v_mul_i32_i24_e32 v14, 0x1800, v14
	v_ashrrev_i32_e32 v15, 31, v14
	v_lshl_add_u64 v[20:21], v[14:15], 2, s[22:23]
	ds_bpermute_b32 v14, v108, v0
	v_lshl_add_u64 v[18:19], v[20:21], 0, s[10:11]
	v_mov_b32_e32 v85, v1
	v_lshl_add_u64 v[26:27], v[18:19], 0, v[84:85]
	ds_read_b128 v[28:31], v222 offset:4096
	s_waitcnt lgkmcnt(0)
	v_add_f32_e32 v0, v0, v14
	ds_bpermute_b32 v14, v109, v0
	v_lshl_add_u64 v[26:27], v[20:21], 0, v[84:85]
	ds_read_b128 v[32:35], v222
	v_ashrrev_i32_e32 v93, 31, v92
	v_lshlrev_b64 v[36:37], 11, v[92:93]
	s_waitcnt lgkmcnt(0)
	v_add_f32_e32 v0, v0, v14
	ds_bpermute_b32 v14, v110, v0
	v_mov_b32_e32 v87, v1
	v_mov_b32_e32 v89, v1
	v_mov_b32_e32 v91, v1
	s_waitcnt lgkmcnt(0)
	v_add_f32_e32 v0, v0, v14
	ds_bpermute_b32 v14, v111, v0
	s_waitcnt lgkmcnt(0)
	v_add_f32_e32 v0, v0, v14
	ds_bpermute_b32 v14, v112, v0
	s_waitcnt lgkmcnt(0)
	v_add_f32_e32 v0, v0, v14
	ds_bpermute_b32 v14, v113, v0
	s_waitcnt lgkmcnt(0)
	v_add_f32_e32 v0, v0, v14
	v_fmamk_f32 v0, v0, 0x3a800000, v218
	v_cmp_gt_f32_e32 vcc, s13, v0
	v_mul_f32_e32 v14, 0x4b800000, v0
	s_nop 0
	v_cndmask_b32_e32 v0, v0, v14, vcc
	v_rsq_f32_e32 v0, v0
	s_nop 0
	v_mul_f32_e32 v14, 0x45800000, v0
	v_cndmask_b32_e32 v0, v0, v14, vcc
	ds_read_b128 v[14:17], v242
	v_mov_b32_e32 v87, v1
	v_mov_b32_e32 v89, v1
	v_mov_b32_e32 v91, v1
	ds_read_b128 v[168:171], v242 offset:1024
	v_lshl_add_u64 v[172:173], v[18:19], 0, v[86:87]
	ds_read_b128 v[172:175], v222 offset:5120
	ds_read_b128 v[176:179], v222 offset:1024
	ds_read_b128 v[180:183], v242 offset:2048
	v_lshl_add_u64 v[184:185], v[18:19], 0, v[88:89]
	ds_read_b128 v[184:187], v222 offset:6144
	ds_read_b128 v[188:191], v222 offset:2048
	ds_read_b128 v[192:195], v242 offset:3072
	v_lshl_add_u64 v[196:197], v[18:19], 0, v[90:91]
	ds_read_b128 v[196:199], v222 offset:7168
	ds_read_b128 v[200:203], v222 offset:3072
	v_pk_mul_f32 v[20:21], v[24:25], v[0:1] op_sel_hi:[1,0]
	v_pk_mul_f32 v[22:23], v[22:23], v[0:1] op_sel_hi:[1,0]
	v_pk_mul_f32 v[12:13], v[12:13], v[0:1] op_sel_hi:[1,0]
	v_pk_mul_f32 v[10:11], v[10:11], v[0:1] op_sel_hi:[1,0]
	v_pk_mul_f32 v[8:9], v[8:9], v[0:1] op_sel_hi:[1,0]
	v_pk_mul_f32 v[6:7], v[6:7], v[0:1] op_sel_hi:[1,0]
	v_pk_mul_f32 v[4:5], v[4:5], v[0:1] op_sel_hi:[1,0]
	v_pk_mul_f32 v[2:3], v[2:3], v[0:1] op_sel_hi:[1,0]
	s_waitcnt lgkmcnt(0)
	v_pk_mul_f32 v[14:15], v[14:15], v[22:23]
	v_pk_mul_f32 v[16:17], v[16:17], v[20:21]
	v_pk_add_f32 v[20:21], v[30:31], 1.0 op_sel_hi:[1,0]
	v_pk_add_f32 v[22:23], v[28:29], 1.0 op_sel_hi:[1,0]
	v_pk_fma_f32 v[16:17], v[20:21], v[16:17], v[34:35]
	v_pk_fma_f32 v[14:15], v[22:23], v[14:15], v[32:33]
	v_lshl_add_u64 v[20:21], v[80:81], 0, v[36:37]
	v_cvt_pk_bf16_f32 v14, v14, v15
	v_cvt_pk_bf16_f32 v15, v16, v17
	global_store_dwordx2 v[20:21], v[14:15], off
	v_lshl_add_u64 v[22:23], v[18:19], 0, v[86:87]
	s_waitcnt lgkmcnt(0)
	v_pk_mul_f32 v[10:11], v[168:169], v[10:11]
	v_pk_mul_f32 v[12:13], v[170:171], v[12:13]
	v_pk_add_f32 v[14:15], v[174:175], 1.0 op_sel_hi:[1, 0]
	v_pk_add_f32 v[16:17], v[172:173], 1.0 op_sel_hi:[1, 0]
	v_pk_fma_f32 v[12:13], v[14:15], v[12:13], v[178:179]
	v_pk_fma_f32 v[10:11], v[16:17], v[10:11], v[176:177]
	v_lshl_add_u64 v[14:15], v[18:19], 0, v[88:89]
	v_cvt_pk_bf16_f32 v10, v10, v11
	v_cvt_pk_bf16_f32 v11, v12, v13
	global_store_dwordx2 v[20:21], v[10:11], off offset:512
	s_waitcnt lgkmcnt(0)
	v_pk_mul_f32 v[6:7], v[180:181], v[6:7]
	v_pk_mul_f32 v[8:9], v[182:183], v[8:9]
	v_pk_add_f32 v[10:11], v[186:187], 1.0 op_sel_hi:[1, 0]
	v_pk_add_f32 v[12:13], v[184:185], 1.0 op_sel_hi:[1, 0]
	v_pk_fma_f32 v[8:9], v[10:11], v[8:9], v[190:191]
	v_pk_fma_f32 v[6:7], v[12:13], v[6:7], v[188:189]
	v_lshl_add_u64 v[10:11], v[18:19], 0, v[90:91]
	v_cvt_pk_bf16_f32 v6, v6, v7
	v_cvt_pk_bf16_f32 v7, v8, v9
	global_store_dwordx2 v[20:21], v[6:7], off offset:1024
	s_waitcnt lgkmcnt(0)
	v_pk_mul_f32 v[2:3], v[2:3], v[192:193]
	v_pk_mul_f32 v[4:5], v[4:5], v[194:195]
	v_pk_add_f32 v[6:7], v[198:199], 1.0 op_sel_hi:[1, 0]
	v_pk_add_f32 v[8:9], v[196:197], 1.0 op_sel_hi:[1, 0]
	v_pk_fma_f32 v[4:5], v[4:5], v[6:7], v[202:203]
	v_pk_fma_f32 v[2:3], v[2:3], v[8:9], v[200:201]
	s_nop 0
	v_cvt_pk_bf16_f32 v2, v2, v3
	v_cvt_pk_bf16_f32 v3, v4, v5
	global_store_dwordx2 v[20:21], v[2:3], off offset:1536
	s_branch .LBB0_442
	s_nop 0
	s_nop 0
	s_nop 0
	s_nop 0
	s_nop 0
	s_nop 0
	s_nop 0
	s_nop 0
	s_nop 0
	s_nop 0
	s_nop 0
	s_nop 0
	s_nop 0
	s_nop 0
	s_nop 0
	s_nop 0
	s_nop 0
	s_nop 0
	s_nop 0
	s_nop 0
	s_nop 0
	s_nop 0
	s_nop 0
	s_nop 0
	s_nop 0
	s_nop 0
	s_nop 0
	s_nop 0
	s_nop 0
	s_nop 0
	s_nop 0
	s_nop 0
	s_nop 0
	s_nop 0
	s_nop 0
	s_nop 0
	s_nop 0
	s_nop 0
	s_nop 0
	s_nop 0
	s_nop 0
	s_nop 0
	s_nop 0
	s_nop 0
	s_nop 0
	s_nop 0
	s_nop 0
	s_nop 0
	s_nop 0
	s_nop 0
	s_nop 0
	s_nop 0
	s_nop 0
	s_nop 0
	s_nop 0
	s_nop 0
	s_nop 0
	s_nop 0
	s_nop 0
	s_nop 0
	s_nop 0
	s_nop 0
	s_nop 0
	s_nop 0
	s_nop 0
	s_nop 0
	s_nop 0
	s_nop 0
	s_nop 0
	s_nop 0
	s_nop 0
	s_nop 0
	s_nop 0
	s_nop 0
	s_nop 0
	s_nop 0

.LBB0_562:
	s_or_b64 exec, exec, s[34:35]
	v_min_i32_e32 v0, 0x8000, v66
	v_ashrrev_i32_e32 v0, 12, v0
	v_lshl_add_u32 v222, v0, 13, v223
	v_mul_i32_i24_e32 v92, 0x1800, v0
	v_ashrrev_i32_e32 v93, 31, v92
	v_lshl_add_u64 v[100:101], v[92:93], 2, s[44:45]
	s_mov_b64 s[8:9], 0x1000
	v_lshl_add_u64 v[112:113], v[100:101], 0, s[8:9]
	v_mov_b32_e32 v79, v1
	v_lshl_add_u64 v[96:97], v[112:113], 0, v[78:79]
	ds_read_b128 v[92:95], v242
	v_lshl_add_u64 v[100:101], v[100:101], 0, v[78:79]
	ds_read_b128 v[96:99], v222 offset:4096
	s_waitcnt vmcnt(0) lgkmcnt(0)
	v_mul_f32_e32 v0, v39, v39
	ds_read_b128 v[108:111], v222
	v_mov_b32_e32 v81, v1
	v_mov_b32_e32 v83, v1
	v_mov_b32_e32 v85, v1
	ds_read_b128 v[168:171], v242 offset:1024
	v_lshl_add_u64 v[172:173], v[112:113], 0, v[80:81]
	ds_read_b128 v[172:175], v222 offset:5120
	ds_read_b128 v[176:179], v222 offset:1024
	ds_read_b128 v[180:183], v242 offset:2048
	v_lshl_add_u64 v[184:185], v[112:113], 0, v[82:83]
	ds_read_b128 v[184:187], v222 offset:6144
	ds_read_b128 v[188:191], v222 offset:2048
	ds_read_b128 v[192:195], v242 offset:3072
	v_lshl_add_u64 v[196:197], v[112:113], 0, v[84:85]
	ds_read_b128 v[196:199], v222 offset:7168
	ds_read_b128 v[200:203], v222 offset:3072
	v_mul_f32_e32 v81, v23, v23
	v_mul_f32_e32 v83, v7, v7
	v_fmac_f32_e32 v0, v38, v38
	v_fmac_f32_e32 v81, v22, v22
	v_mul_f32_e32 v85, v3, v3
	v_fmac_f32_e32 v83, v6, v6
	v_fmac_f32_e32 v0, v40, v40
	v_fmac_f32_e32 v81, v24, v24
	v_fmac_f32_e32 v85, v2, v2
	v_fmac_f32_e32 v83, v8, v8
	v_fmac_f32_e32 v0, v41, v41
	v_fmac_f32_e32 v81, v25, v25
	v_fmac_f32_e32 v85, v4, v4
	v_fmac_f32_e32 v83, v9, v9
	v_add_f32_e32 v0, v81, v0
	v_fmac_f32_e32 v85, v5, v5
	v_add_f32_e32 v0, v83, v0
	v_add_f32_e32 v0, v85, v0
	ds_bpermute_b32 v81, v102, v0
	v_mov_b32_e32 v85, v1
	s_waitcnt lgkmcnt(0)
	v_add_f32_e32 v0, v0, v81
	ds_bpermute_b32 v81, v103, v0
	s_waitcnt lgkmcnt(0)
	v_add_f32_e32 v0, v0, v81
	ds_bpermute_b32 v81, v104, v0
	s_waitcnt lgkmcnt(0)
	v_add_f32_e32 v0, v0, v81
	ds_bpermute_b32 v81, v105, v0
	s_waitcnt lgkmcnt(0)
	v_add_f32_e32 v0, v0, v81
	ds_bpermute_b32 v81, v106, v0
	s_waitcnt lgkmcnt(0)
	v_add_f32_e32 v0, v0, v81
	ds_bpermute_b32 v81, v107, v0
	s_waitcnt lgkmcnt(0)
	v_add_f32_e32 v0, v0, v81
	v_fmamk_f32 v0, v0, 0x3a800000, v218
	v_mul_f32_e32 v81, 0x4b800000, v0
	v_cmp_gt_f32_e32 vcc, s13, v0
	s_nop 1
	v_cndmask_b32_e32 v0, v0, v81, vcc
	v_rsq_f32_e32 v0, v0
	v_mov_b32_e32 v81, v1
	v_mul_f32_e32 v83, 0x45800000, v0
	v_cndmask_b32_e32 v0, v0, v83, vcc
	v_pk_mul_f32 v[40:41], v[40:41], v[0:1] op_sel_hi:[1,0]
	v_pk_mul_f32 v[38:39], v[38:39], v[0:1] op_sel_hi:[1,0]
	v_pk_mul_f32 v[24:25], v[24:25], v[0:1] op_sel_hi:[1,0]
	v_pk_mul_f32 v[22:23], v[22:23], v[0:1] op_sel_hi:[1,0]
	v_mov_b32_e32 v83, v1
	v_pk_mul_f32 v[8:9], v[8:9], v[0:1] op_sel_hi:[1,0]
	v_pk_mul_f32 v[6:7], v[6:7], v[0:1] op_sel_hi:[1,0]
	v_pk_mul_f32 v[4:5], v[4:5], v[0:1] op_sel_hi:[1,0]
	v_pk_mul_f32 v[2:3], v[2:3], v[0:1] op_sel_hi:[1,0]
	v_pk_mul_f32 v[38:39], v[92:93], v[38:39]
	v_pk_mul_f32 v[40:41], v[94:95], v[40:41]
	v_pk_add_f32 v[92:93], v[98:99], 1.0 op_sel_hi:[1,0]
	v_pk_add_f32 v[94:95], v[96:97], 1.0 op_sel_hi:[1,0]
	s_waitcnt lgkmcnt(0)
	v_pk_fma_f32 v[40:41], v[92:93], v[40:41], v[110:111]
	v_pk_fma_f32 v[38:39], v[94:95], v[38:39], v[108:109]
	v_lshl_add_u64 v[92:93], v[112:113], 0, v[80:81]
	v_cvt_pk_bf16_f32 v38, v38, v39
	v_cvt_pk_bf16_f32 v39, v40, v41
	global_store_dwordx2 v[76:77], v[38:39], off
	v_cmp_gt_i32_e32 vcc, s15, v86
	s_waitcnt lgkmcnt(0)
	v_pk_mul_f32 v[22:23], v[168:169], v[22:23]
	v_pk_mul_f32 v[24:25], v[170:171], v[24:25]
	v_pk_add_f32 v[38:39], v[174:175], 1.0 op_sel_hi:[1, 0]
	v_pk_add_f32 v[40:41], v[172:173], 1.0 op_sel_hi:[1, 0]
	v_pk_fma_f32 v[24:25], v[38:39], v[24:25], v[178:179]
	v_pk_fma_f32 v[22:23], v[40:41], v[22:23], v[176:177]
	v_lshl_add_u64 v[38:39], v[112:113], 0, v[82:83]
	v_cvt_pk_bf16_f32 v22, v22, v23
	v_cvt_pk_bf16_f32 v23, v24, v25
	global_store_dwordx2 v[76:77], v[22:23], off offset:512
	s_waitcnt lgkmcnt(0)
	v_pk_mul_f32 v[6:7], v[180:181], v[6:7]
	v_pk_mul_f32 v[8:9], v[182:183], v[8:9]
	v_pk_add_f32 v[22:23], v[186:187], 1.0 op_sel_hi:[1, 0]
	v_pk_add_f32 v[24:25], v[184:185], 1.0 op_sel_hi:[1, 0]
	v_pk_fma_f32 v[8:9], v[22:23], v[8:9], v[190:191]
	v_pk_fma_f32 v[6:7], v[24:25], v[6:7], v[188:189]
	v_lshl_add_u64 v[22:23], v[112:113], 0, v[84:85]
	v_cvt_pk_bf16_f32 v6, v6, v7
	v_cvt_pk_bf16_f32 v7, v8, v9
	global_store_dwordx2 v[76:77], v[6:7], off offset:1024
	s_waitcnt lgkmcnt(0)
	v_pk_mul_f32 v[2:3], v[2:3], v[192:193]
	v_pk_mul_f32 v[4:5], v[4:5], v[194:195]
	v_pk_add_f32 v[6:7], v[198:199], 1.0 op_sel_hi:[1, 0]
	v_pk_add_f32 v[8:9], v[196:197], 1.0 op_sel_hi:[1, 0]
	v_pk_fma_f32 v[4:5], v[4:5], v[6:7], v[202:203]
	v_pk_fma_f32 v[2:3], v[2:3], v[8:9], v[200:201]
	s_nop 0
	v_cvt_pk_bf16_f32 v2, v2, v3
	v_cvt_pk_bf16_f32 v3, v4, v5
	global_store_dwordx2 v[76:77], v[2:3], off offset:1536
	s_and_saveexec_b64 s[34:35], vcc
	s_cbranch_execz .LBB0_565
	v_min_i32_e32 v0, 0x8000, v86
	v_ashrrev_i32_e32 v0, 12, v0
	v_lshl_add_u32 v222, v0, 13, v223
	v_mul_i32_i24_e32 v2, 0x1800, v0
	v_ashrrev_i32_e32 v3, 31, v2
	v_lshl_add_u64 v[22:23], v[2:3], 2, s[44:45]
	v_lshl_add_u64 v[38:39], v[22:23], 0, s[8:9]
	v_lshl_add_u64 v[6:7], v[38:39], 0, v[78:79]
	ds_read_b128 v[2:5], v242
	v_lshl_add_u64 v[40:41], v[22:23], 0, v[78:79]
	ds_read_b128 v[6:9], v222 offset:4096
	v_mul_f32_e32 v0, v35, v35
	ds_read_b128 v[22:25], v222
	v_mov_b32_e32 v81, v1
	v_mov_b32_e32 v83, v1
	v_mov_b32_e32 v85, v1
	ds_read_b128 v[168:171], v242 offset:1024
	v_lshl_add_u64 v[172:173], v[38:39], 0, v[80:81]
	ds_read_b128 v[172:175], v222 offset:5120
	ds_read_b128 v[176:179], v222 offset:1024
	ds_read_b128 v[180:183], v242 offset:2048
	v_lshl_add_u64 v[184:185], v[38:39], 0, v[82:83]
	ds_read_b128 v[184:187], v222 offset:6144
	ds_read_b128 v[188:191], v222 offset:2048
	ds_read_b128 v[192:195], v242 offset:3072
	v_lshl_add_u64 v[196:197], v[38:39], 0, v[84:85]
	ds_read_b128 v[196:199], v222 offset:7168
	ds_read_b128 v[200:203], v222 offset:3072
	v_mul_f32_e32 v79, v31, v31
	v_mul_f32_e32 v87, v19, v19
	v_fmac_f32_e32 v0, v34, v34
	v_fmac_f32_e32 v79, v30, v30
	v_mul_f32_e32 v89, v11, v11
	v_fmac_f32_e32 v87, v18, v18
	v_fmac_f32_e32 v0, v36, v36
	v_fmac_f32_e32 v79, v32, v32
	v_fmac_f32_e32 v89, v10, v10
	v_fmac_f32_e32 v87, v20, v20
	v_fmac_f32_e32 v0, v37, v37
	v_fmac_f32_e32 v79, v33, v33
	v_fmac_f32_e32 v89, v12, v12
	v_fmac_f32_e32 v87, v21, v21
	v_add_f32_e32 v0, v79, v0
	v_fmac_f32_e32 v89, v13, v13
	v_add_f32_e32 v0, v87, v0
	v_add_f32_e32 v0, v89, v0
	ds_bpermute_b32 v79, v102, v0
	v_ashrrev_i32_e32 v87, 31, v86
	v_lshlrev_b64 v[86:87], 11, v[86:87]
	v_lshl_add_u64 v[86:87], v[74:75], 0, v[86:87]
	s_waitcnt lgkmcnt(0)
	v_add_f32_e32 v0, v0, v79
	ds_bpermute_b32 v79, v103, v0
	s_waitcnt lgkmcnt(0)
	v_add_f32_e32 v0, v0, v79
	ds_bpermute_b32 v79, v104, v0
	s_waitcnt lgkmcnt(0)
	v_add_f32_e32 v0, v0, v79
	ds_bpermute_b32 v79, v105, v0
	s_waitcnt lgkmcnt(0)
	v_add_f32_e32 v0, v0, v79
	ds_bpermute_b32 v79, v106, v0
	s_waitcnt lgkmcnt(0)
	v_add_f32_e32 v0, v0, v79
	ds_bpermute_b32 v79, v107, v0
	s_waitcnt lgkmcnt(0)
	v_add_f32_e32 v0, v0, v79
	v_fmamk_f32 v0, v0, 0x3a800000, v218
	v_mul_f32_e32 v79, 0x4b800000, v0
	v_cmp_gt_f32_e32 vcc, s13, v0
	s_waitcnt lgkmcnt(0)
	v_pk_add_f32 v[8:9], v[8:9], 1.0 op_sel_hi:[1,0]
	v_cndmask_b32_e32 v0, v0, v79, vcc
	v_rsq_f32_e32 v0, v0
	v_pk_add_f32 v[6:7], v[6:7], 1.0 op_sel_hi:[1,0]
	v_mul_f32_e32 v79, 0x45800000, v0
	v_cndmask_b32_e32 v0, v0, v79, vcc
	v_pk_mul_f32 v[36:37], v[36:37], v[0:1] op_sel_hi:[1,0]
	v_pk_mul_f32 v[34:35], v[34:35], v[0:1] op_sel_hi:[1,0]
	v_pk_mul_f32 v[4:5], v[4:5], v[36:37]
	v_pk_mul_f32 v[2:3], v[2:3], v[34:35]
	s_waitcnt lgkmcnt(0)
	v_pk_fma_f32 v[4:5], v[8:9], v[4:5], v[24:25]
	v_pk_fma_f32 v[2:3], v[6:7], v[2:3], v[22:23]
	v_lshl_add_u64 v[6:7], v[38:39], 0, v[80:81]
	v_cvt_pk_bf16_f32 v2, v2, v3
	v_cvt_pk_bf16_f32 v3, v4, v5
	global_store_dwordx2 v[86:87], v[2:3], off
	v_pk_mul_f32 v[32:33], v[32:33], v[0:1] op_sel_hi:[1,0]
	v_pk_mul_f32 v[30:31], v[30:31], v[0:1] op_sel_hi:[1,0]
	v_pk_mul_f32 v[20:21], v[20:21], v[0:1] op_sel_hi:[1,0]
	v_pk_mul_f32 v[18:19], v[18:19], v[0:1] op_sel_hi:[1,0]
	v_pk_mul_f32 v[12:13], v[12:13], v[0:1] op_sel_hi:[1,0]
	v_pk_mul_f32 v[10:11], v[10:11], v[0:1] op_sel_hi:[1,0]
	s_waitcnt lgkmcnt(0)
	v_pk_add_f32 v[8:9], v[174:175], 1.0 op_sel_hi:[1, 0]
	v_pk_mul_f32 v[2:3], v[168:169], v[30:31]
	v_pk_mul_f32 v[4:5], v[170:171], v[32:33]
	v_pk_add_f32 v[6:7], v[172:173], 1.0 op_sel_hi:[1, 0]
	v_pk_fma_f32 v[4:5], v[8:9], v[4:5], v[178:179]
	v_pk_fma_f32 v[2:3], v[6:7], v[2:3], v[176:177]
	v_lshl_add_u64 v[6:7], v[38:39], 0, v[82:83]
	v_cvt_pk_bf16_f32 v2, v2, v3
	v_cvt_pk_bf16_f32 v3, v4, v5
	global_store_dwordx2 v[86:87], v[2:3], off offset:512
	s_waitcnt lgkmcnt(0)
	v_pk_add_f32 v[8:9], v[186:187], 1.0 op_sel_hi:[1, 0]
	v_pk_mul_f32 v[2:3], v[180:181], v[18:19]
	v_pk_mul_f32 v[4:5], v[182:183], v[20:21]
	v_pk_add_f32 v[6:7], v[184:185], 1.0 op_sel_hi:[1, 0]
	v_pk_fma_f32 v[4:5], v[8:9], v[4:5], v[190:191]
	v_pk_fma_f32 v[2:3], v[6:7], v[2:3], v[188:189]
	v_lshl_add_u64 v[6:7], v[38:39], 0, v[84:85]
	v_cvt_pk_bf16_f32 v2, v2, v3
	v_cvt_pk_bf16_f32 v3, v4, v5
	global_store_dwordx2 v[86:87], v[2:3], off offset:1024
	s_waitcnt lgkmcnt(0)
	v_pk_add_f32 v[8:9], v[198:199], 1.0 op_sel_hi:[1, 0]
	v_pk_mul_f32 v[2:3], v[10:11], v[192:193]
	v_pk_mul_f32 v[4:5], v[12:13], v[194:195]
	v_pk_add_f32 v[6:7], v[196:197], 1.0 op_sel_hi:[1, 0]
	v_pk_fma_f32 v[4:5], v[4:5], v[8:9], v[202:203]
	v_pk_fma_f32 v[2:3], v[2:3], v[6:7], v[200:201]
	s_nop 0
	v_cvt_pk_bf16_f32 v2, v2, v3
	v_cvt_pk_bf16_f32 v3, v4, v5
	global_store_dwordx2 v[86:87], v[2:3], off offset:1536
	s_or_b64 exec, exec, s[34:35]
	v_cmp_gt_i32_e32 vcc, s15, v88
	s_and_saveexec_b64 s[34:35], vcc
	s_cbranch_execnz .LBB0_566

.LBB0_566:
	v_min_i32_e32 v0, 0x8000, v88
	v_ashrrev_i32_e32 v0, 12, v0
	v_lshl_add_u32 v222, v0, 13, v223
	v_mul_i32_i24_e32 v2, 0x1800, v0
	v_ashrrev_i32_e32 v3, 31, v2
	v_lshl_add_u64 v[10:11], v[2:3], 2, s[44:45]
	v_lshl_add_u64 v[18:19], v[10:11], 0, s[8:9]
	v_mov_b32_e32 v79, v1
	v_lshl_add_u64 v[6:7], v[18:19], 0, v[78:79]
	ds_read_b128 v[2:5], v242
	v_lshl_add_u64 v[20:21], v[10:11], 0, v[78:79]
	ds_read_b128 v[6:9], v222 offset:4096
	v_mul_f32_e32 v0, v47, v47
	ds_read_b128 v[10:13], v222
	v_mov_b32_e32 v81, v1
	v_mov_b32_e32 v83, v1
	v_mov_b32_e32 v85, v1
	ds_read_b128 v[168:171], v242 offset:1024
	v_lshl_add_u64 v[172:173], v[18:19], 0, v[80:81]
	ds_read_b128 v[172:175], v222 offset:5120
	ds_read_b128 v[176:179], v222 offset:1024
	ds_read_b128 v[180:183], v242 offset:2048
	v_lshl_add_u64 v[184:185], v[18:19], 0, v[82:83]
	ds_read_b128 v[184:187], v222 offset:6144
	ds_read_b128 v[188:191], v222 offset:2048
	ds_read_b128 v[192:195], v242 offset:3072
	v_lshl_add_u64 v[196:197], v[18:19], 0, v[84:85]
	ds_read_b128 v[196:199], v222 offset:7168
	ds_read_b128 v[200:203], v222 offset:3072
	v_mul_f32_e32 v22, v43, v43
	v_mul_f32_e32 v23, v27, v27
	v_fmac_f32_e32 v0, v46, v46
	v_fmac_f32_e32 v22, v42, v42
	v_mul_f32_e32 v24, v15, v15
	v_fmac_f32_e32 v23, v26, v26
	v_fmac_f32_e32 v0, v48, v48
	v_fmac_f32_e32 v22, v44, v44
	v_fmac_f32_e32 v24, v14, v14
	v_fmac_f32_e32 v23, v28, v28
	v_fmac_f32_e32 v0, v49, v49
	v_fmac_f32_e32 v22, v45, v45
	v_fmac_f32_e32 v24, v16, v16
	v_fmac_f32_e32 v23, v29, v29
	v_add_f32_e32 v0, v22, v0
	v_fmac_f32_e32 v24, v17, v17
	v_add_f32_e32 v0, v23, v0
	v_add_f32_e32 v0, v24, v0
	ds_bpermute_b32 v22, v102, v0
	v_ashrrev_i32_e32 v89, 31, v88
	v_mov_b32_e32 v81, v1
	v_mov_b32_e32 v83, v1
	v_mov_b32_e32 v85, v1
	s_waitcnt lgkmcnt(0)
	v_add_f32_e32 v0, v0, v22
	ds_bpermute_b32 v22, v103, v0
	s_waitcnt lgkmcnt(0)
	v_add_f32_e32 v0, v0, v22
	ds_bpermute_b32 v22, v104, v0
	s_waitcnt lgkmcnt(0)
	v_add_f32_e32 v0, v0, v22
	ds_bpermute_b32 v22, v105, v0
	s_waitcnt lgkmcnt(0)
	v_add_f32_e32 v0, v0, v22
	ds_bpermute_b32 v22, v106, v0
	s_waitcnt lgkmcnt(0)
	v_add_f32_e32 v0, v0, v22
	ds_bpermute_b32 v22, v107, v0
	s_waitcnt lgkmcnt(0)
	v_add_f32_e32 v0, v0, v22
	v_fmamk_f32 v0, v0, 0x3a800000, v218
	v_mul_f32_e32 v22, 0x4b800000, v0
	v_cmp_gt_f32_e32 vcc, s13, v0
	s_waitcnt lgkmcnt(0)
	v_pk_add_f32 v[8:9], v[8:9], 1.0 op_sel_hi:[1,0]
	v_cndmask_b32_e32 v0, v0, v22, vcc
	v_rsq_f32_e32 v0, v0
	v_pk_add_f32 v[6:7], v[6:7], 1.0 op_sel_hi:[1,0]
	v_lshlrev_b64 v[22:23], 11, v[88:89]
	v_lshl_add_u64 v[22:23], v[74:75], 0, v[22:23]
	v_mul_f32_e32 v24, 0x45800000, v0
	v_cndmask_b32_e32 v0, v0, v24, vcc
	v_pk_mul_f32 v[24:25], v[48:49], v[0:1] op_sel_hi:[1,0]
	v_pk_mul_f32 v[30:31], v[46:47], v[0:1] op_sel_hi:[1,0]
	v_pk_mul_f32 v[4:5], v[4:5], v[24:25]
	v_pk_mul_f32 v[2:3], v[2:3], v[30:31]
	s_waitcnt lgkmcnt(0)
	v_pk_fma_f32 v[4:5], v[8:9], v[4:5], v[12:13]
	v_pk_fma_f32 v[2:3], v[6:7], v[2:3], v[10:11]
	v_lshl_add_u64 v[6:7], v[18:19], 0, v[80:81]
	v_cvt_pk_bf16_f32 v2, v2, v3
	v_cvt_pk_bf16_f32 v3, v4, v5
	global_store_dwordx2 v[22:23], v[2:3], off
	v_pk_mul_f32 v[24:25], v[44:45], v[0:1] op_sel_hi:[1,0]
	v_pk_mul_f32 v[30:31], v[42:43], v[0:1] op_sel_hi:[1,0]
	v_pk_mul_f32 v[26:27], v[26:27], v[0:1] op_sel_hi:[1,0]
	v_pk_mul_f32 v[16:17], v[16:17], v[0:1] op_sel_hi:[1,0]
	v_pk_mul_f32 v[14:15], v[14:15], v[0:1] op_sel_hi:[1,0]
	s_waitcnt lgkmcnt(0)
	v_pk_add_f32 v[8:9], v[174:175], 1.0 op_sel_hi:[1, 0]
	v_pk_mul_f32 v[2:3], v[168:169], v[30:31]
	v_pk_mul_f32 v[4:5], v[170:171], v[24:25]
	v_pk_add_f32 v[6:7], v[172:173], 1.0 op_sel_hi:[1, 0]
	v_pk_fma_f32 v[4:5], v[8:9], v[4:5], v[178:179]
	v_pk_fma_f32 v[2:3], v[6:7], v[2:3], v[176:177]
	v_lshl_add_u64 v[6:7], v[18:19], 0, v[82:83]
	v_cvt_pk_bf16_f32 v2, v2, v3
	v_cvt_pk_bf16_f32 v3, v4, v5
	global_store_dwordx2 v[22:23], v[2:3], off offset:512
	v_pk_mul_f32 v[24:25], v[28:29], v[0:1] op_sel_hi:[1,0]
	s_waitcnt lgkmcnt(0)
	v_pk_add_f32 v[8:9], v[186:187], 1.0 op_sel_hi:[1, 0]
	v_pk_mul_f32 v[2:3], v[180:181], v[26:27]
	v_pk_mul_f32 v[4:5], v[182:183], v[24:25]
	v_pk_add_f32 v[6:7], v[184:185], 1.0 op_sel_hi:[1, 0]
	v_pk_fma_f32 v[4:5], v[8:9], v[4:5], v[190:191]
	v_pk_fma_f32 v[2:3], v[6:7], v[2:3], v[188:189]
	v_lshl_add_u64 v[6:7], v[18:19], 0, v[84:85]
	v_cvt_pk_bf16_f32 v2, v2, v3
	v_cvt_pk_bf16_f32 v3, v4, v5
	global_store_dwordx2 v[22:23], v[2:3], off offset:1024
	s_waitcnt lgkmcnt(0)
	v_pk_add_f32 v[8:9], v[198:199], 1.0 op_sel_hi:[1, 0]
	v_pk_mul_f32 v[2:3], v[14:15], v[192:193]
	v_pk_mul_f32 v[4:5], v[16:17], v[194:195]
	v_pk_add_f32 v[6:7], v[196:197], 1.0 op_sel_hi:[1, 0]
	v_pk_fma_f32 v[4:5], v[4:5], v[8:9], v[202:203]
	v_pk_fma_f32 v[2:3], v[2:3], v[6:7], v[200:201]
	s_nop 0
	v_cvt_pk_bf16_f32 v2, v2, v3
	v_cvt_pk_bf16_f32 v3, v4, v5
	global_store_dwordx2 v[22:23], v[2:3], off offset:1536
	s_or_b64 exec, exec, s[34:35]
	v_cmp_gt_i32_e32 vcc, s15, v90
	s_and_saveexec_b64 s[34:35], vcc
	s_cbranch_execz .LBB0_529
.LBB0_567:
	v_min_i32_e32 v0, 0x8000, v90
	v_ashrrev_i32_e32 v0, 12, v0
	v_lshl_add_u32 v222, v0, 13, v223
	v_mul_i32_i24_e32 v2, 0x1800, v0
	v_ashrrev_i32_e32 v3, 31, v2
	v_lshl_add_u64 v[10:11], v[2:3], 2, s[44:45]
	v_lshl_add_u64 v[14:15], v[10:11], 0, s[8:9]
	v_mov_b32_e32 v79, v1
	v_lshl_add_u64 v[6:7], v[14:15], 0, v[78:79]
	ds_read_b128 v[2:5], v242
	v_lshl_add_u64 v[16:17], v[10:11], 0, v[78:79]
	ds_read_b128 v[6:9], v222 offset:4096
	v_mul_f32_e32 v0, v63, v63
	ds_read_b128 v[10:13], v222
	v_mov_b32_e32 v81, v1
	v_mov_b32_e32 v83, v1
	v_mov_b32_e32 v85, v1
	ds_read_b128 v[168:171], v242 offset:1024
	v_lshl_add_u64 v[172:173], v[14:15], 0, v[80:81]
	ds_read_b128 v[172:175], v222 offset:5120
	ds_read_b128 v[176:179], v222 offset:1024
	ds_read_b128 v[180:183], v242 offset:2048
	v_lshl_add_u64 v[184:185], v[14:15], 0, v[82:83]
	ds_read_b128 v[184:187], v222 offset:6144
	ds_read_b128 v[188:191], v222 offset:2048
	ds_read_b128 v[192:195], v242 offset:3072
	v_lshl_add_u64 v[196:197], v[14:15], 0, v[84:85]
	ds_read_b128 v[196:199], v222 offset:7168
	ds_read_b128 v[200:203], v222 offset:3072
	v_mul_f32_e32 v18, v59, v59
	v_mul_f32_e32 v19, v55, v55
	v_fmac_f32_e32 v0, v62, v62
	v_fmac_f32_e32 v18, v58, v58
	v_mul_f32_e32 v20, v51, v51
	v_fmac_f32_e32 v19, v54, v54
	v_fmac_f32_e32 v0, v64, v64
	v_fmac_f32_e32 v18, v60, v60
	v_fmac_f32_e32 v20, v50, v50
	v_fmac_f32_e32 v19, v56, v56
	v_fmac_f32_e32 v0, v65, v65
	v_fmac_f32_e32 v18, v61, v61
	v_fmac_f32_e32 v20, v52, v52
	v_fmac_f32_e32 v19, v57, v57
	v_add_f32_e32 v0, v18, v0
	v_fmac_f32_e32 v20, v53, v53
	v_add_f32_e32 v0, v19, v0
	v_add_f32_e32 v0, v20, v0
	ds_bpermute_b32 v18, v102, v0
	v_ashrrev_i32_e32 v91, 31, v90
	v_mov_b32_e32 v81, v1
	v_mov_b32_e32 v83, v1
	v_mov_b32_e32 v85, v1
	s_waitcnt lgkmcnt(0)
	v_add_f32_e32 v0, v0, v18
	ds_bpermute_b32 v18, v103, v0
	s_waitcnt lgkmcnt(0)
	v_add_f32_e32 v0, v0, v18
	ds_bpermute_b32 v18, v104, v0
	s_waitcnt lgkmcnt(0)
	v_add_f32_e32 v0, v0, v18
	ds_bpermute_b32 v18, v105, v0
	s_waitcnt lgkmcnt(0)
	v_add_f32_e32 v0, v0, v18
	ds_bpermute_b32 v18, v106, v0
	s_waitcnt lgkmcnt(0)
	v_add_f32_e32 v0, v0, v18
	ds_bpermute_b32 v18, v107, v0
	s_waitcnt lgkmcnt(0)
	v_add_f32_e32 v0, v0, v18
	v_fmamk_f32 v0, v0, 0x3a800000, v218
	v_mul_f32_e32 v18, 0x4b800000, v0
	v_cmp_gt_f32_e32 vcc, s13, v0
	s_waitcnt lgkmcnt(0)
	v_pk_add_f32 v[8:9], v[8:9], 1.0 op_sel_hi:[1,0]
	v_cndmask_b32_e32 v0, v0, v18, vcc
	v_rsq_f32_e32 v0, v0
	v_pk_add_f32 v[6:7], v[6:7], 1.0 op_sel_hi:[1,0]
	v_lshlrev_b64 v[18:19], 11, v[90:91]
	v_lshl_add_u64 v[18:19], v[74:75], 0, v[18:19]
	v_mul_f32_e32 v20, 0x45800000, v0
	v_cndmask_b32_e32 v0, v0, v20, vcc
	v_pk_mul_f32 v[20:21], v[64:65], v[0:1] op_sel_hi:[1,0]
	v_pk_mul_f32 v[22:23], v[62:63], v[0:1] op_sel_hi:[1,0]
	v_pk_mul_f32 v[4:5], v[4:5], v[20:21]
	v_pk_mul_f32 v[2:3], v[2:3], v[22:23]
	s_waitcnt lgkmcnt(0)
	v_pk_fma_f32 v[4:5], v[8:9], v[4:5], v[12:13]
	v_pk_fma_f32 v[2:3], v[6:7], v[2:3], v[10:11]
	v_lshl_add_u64 v[6:7], v[14:15], 0, v[80:81]
	v_cvt_pk_bf16_f32 v2, v2, v3
	v_cvt_pk_bf16_f32 v3, v4, v5
	global_store_dwordx2 v[18:19], v[2:3], off
	v_pk_mul_f32 v[20:21], v[60:61], v[0:1] op_sel_hi:[1,0]
	v_pk_mul_f32 v[22:23], v[58:59], v[0:1] op_sel_hi:[1,0]
	s_waitcnt lgkmcnt(0)
	v_pk_add_f32 v[8:9], v[174:175], 1.0 op_sel_hi:[1, 0]
	v_pk_mul_f32 v[2:3], v[168:169], v[22:23]
	v_pk_mul_f32 v[4:5], v[170:171], v[20:21]
	v_pk_add_f32 v[6:7], v[172:173], 1.0 op_sel_hi:[1, 0]
	v_pk_fma_f32 v[4:5], v[8:9], v[4:5], v[178:179]
	v_pk_fma_f32 v[2:3], v[6:7], v[2:3], v[176:177]
	v_lshl_add_u64 v[6:7], v[14:15], 0, v[82:83]
	v_cvt_pk_bf16_f32 v2, v2, v3
	v_cvt_pk_bf16_f32 v3, v4, v5
	global_store_dwordx2 v[18:19], v[2:3], off offset:512
	v_pk_mul_f32 v[20:21], v[56:57], v[0:1] op_sel_hi:[1,0]
	v_pk_mul_f32 v[22:23], v[54:55], v[0:1] op_sel_hi:[1,0]
	s_waitcnt lgkmcnt(0)
	v_pk_add_f32 v[8:9], v[186:187], 1.0 op_sel_hi:[1, 0]
	v_pk_mul_f32 v[2:3], v[180:181], v[22:23]
	v_pk_mul_f32 v[4:5], v[182:183], v[20:21]
	v_pk_add_f32 v[6:7], v[184:185], 1.0 op_sel_hi:[1, 0]
	v_pk_fma_f32 v[4:5], v[8:9], v[4:5], v[190:191]
	v_pk_fma_f32 v[2:3], v[6:7], v[2:3], v[188:189]
	v_lshl_add_u64 v[6:7], v[14:15], 0, v[84:85]
	v_cvt_pk_bf16_f32 v2, v2, v3
	v_cvt_pk_bf16_f32 v3, v4, v5
	global_store_dwordx2 v[18:19], v[2:3], off offset:1024
	v_pk_mul_f32 v[14:15], v[52:53], v[0:1] op_sel_hi:[1,0]
	v_pk_mul_f32 v[16:17], v[50:51], v[0:1] op_sel_hi:[1,0]
	s_waitcnt lgkmcnt(0)
	v_pk_add_f32 v[8:9], v[198:199], 1.0 op_sel_hi:[1, 0]
	v_pk_mul_f32 v[2:3], v[16:17], v[192:193]
	v_pk_mul_f32 v[4:5], v[14:15], v[194:195]
	v_pk_add_f32 v[6:7], v[196:197], 1.0 op_sel_hi:[1, 0]
	v_pk_fma_f32 v[4:5], v[4:5], v[8:9], v[202:203]
	v_pk_fma_f32 v[2:3], v[2:3], v[6:7], v[200:201]
	s_nop 0
	v_cvt_pk_bf16_f32 v2, v2, v3
	v_cvt_pk_bf16_f32 v3, v4, v5
	global_store_dwordx2 v[18:19], v[2:3], off offset:1536
	s_branch .LBB0_529
	s_nop 0
	s_nop 0
